# v14 + first QK MFMA of each prompt attention step issued at the step head, ahead of the V address VALU and V transpose reads
# speedup vs baseline: 1.0042x; 1.0008x over previous
.LBB0_1068:
	s_waitcnt lgkmcnt(0)
	v_mfma_f32_32x32x16_bf16 v[146:161], v[206:209], v[210:213], v[82:97]
	v_add_u32_e32 v16, s0, v246
	ds_read_b64_tr_b16 v[6:7], v16 offset:49664
	ds_read_b64_tr_b16 v[4:5], v16 offset:49152
	v_add_f32_e32 v2, v114, v115
	v_add_f32_e32 v2, v116, v2
	v_add_f32_e32 v2, v117, v2
	v_add_f32_e32 v2, v118, v2
	v_add_f32_e32 v2, v119, v2
	v_cvt_pk_bf16_f32 v174, v114, v115
	v_cvt_pk_bf16_f32 v175, v116, v117
	ds_read_b64_tr_b16 v[10:11], v16 offset:53760
	ds_read_b64_tr_b16 v[8:9], v16 offset:53248
	ds_read_b128 v[206:209], v244 offset:1024
	v_mfma_f32_32x32x16_bf16 v[130:145], v[202:205], v[210:213], v[82:97]
	v_add_f32_e32 v2, v120, v2
	v_add_f32_e32 v2, v121, v2
	v_add_f32_e32 v2, v122, v2
	v_add_f32_e32 v2, v123, v2
	v_cvt_pk_bf16_f32 v176, v118, v119
	v_cvt_pk_bf16_f32 v177, v120, v121
	ds_read_b64_tr_b16 v[12:13], v16 offset:50176
	ds_read_b64_tr_b16 v[14:15], v16 offset:50688
	s_waitcnt lgkmcnt(2)
	v_mfma_f32_32x32x16_bf16 v[146:161], v[198:201], v[206:209], v[146:161]
	v_add_f32_e32 v2, v124, v2
	v_add_f32_e32 v2, v125, v2
	v_add_f32_e32 v2, v126, v2
	v_add_f32_e32 v2, v127, v2
	v_cvt_pk_bf16_f32 v170, v122, v123
	v_cvt_pk_bf16_f32 v171, v124, v125
	ds_read_b64_tr_b16 v[116:117], v16 offset:54784
	ds_read_b64_tr_b16 v[114:115], v16 offset:54272
	ds_read_b128 v[122:125], v244 offset:2048
	v_mfma_f32_32x32x16_bf16 v[130:145], v[194:197], v[206:209], v[130:145]
	v_add_f32_e32 v2, v128, v2
	v_add_f32_e32 v2, v129, v2
	v_add_f32_e32 v2, v98, v2
	v_add_f32_e32 v2, v99, v2
	v_cvt_pk_bf16_f32 v172, v126, v127
	v_cvt_pk_bf16_f32 v173, v128, v129
	ds_read_b64_tr_b16 v[118:119], v16 offset:51200
	ds_read_b64_tr_b16 v[120:121], v16 offset:51712
	s_waitcnt lgkmcnt(2)
	v_mfma_f32_32x32x16_bf16 v[146:161], v[190:193], v[122:125], v[146:161]
	v_add_f32_e32 v2, v100, v2
	v_add_f32_e32 v2, v101, v2
	v_add_f32_e32 v2, v102, v2
	v_add_f32_e32 v2, v103, v2
	v_cvt_pk_bf16_f32 v166, v98, v99
	v_cvt_pk_bf16_f32 v167, v100, v101
	ds_read_b64_tr_b16 v[100:101], v16 offset:55808
	ds_read_b64_tr_b16 v[98:99], v16 offset:55296
	ds_read_b128 v[126:129], v244 offset:3072
	v_mfma_f32_32x32x16_bf16 v[130:145], v[186:189], v[122:125], v[130:145]
	v_add_f32_e32 v2, v104, v2
	v_add_f32_e32 v2, v105, v2
	v_add_f32_e32 v2, v106, v2
	v_add_f32_e32 v2, v107, v2
	v_cvt_pk_bf16_f32 v168, v102, v103
	v_cvt_pk_bf16_f32 v169, v104, v105
	ds_read_b64_tr_b16 v[102:103], v16 offset:52224
	ds_read_b64_tr_b16 v[104:105], v16 offset:52736
	s_waitcnt lgkmcnt(2)
	v_mfma_f32_32x32x16_bf16 v[146:161], v[182:185], v[126:129], v[146:161]
	v_add_f32_e32 v2, v108, v2
	v_add_f32_e32 v2, v109, v2
	v_add_f32_e32 v2, v110, v2
	v_add_f32_e32 v2, v111, v2
	v_cvt_pk_bf16_f32 v162, v106, v107
	v_cvt_pk_bf16_f32 v163, v108, v109
	ds_read_b64_tr_b16 v[106:107], v16 offset:56320
	ds_read_b64_tr_b16 v[108:109], v16 offset:56832
	v_mfma_f32_32x32x16_bf16 v[130:145], v[178:181], v[126:129], v[130:145]
	v_add_f32_e32 v2, v112, v2
	v_add_f32_e32 v2, v113, v2
	v_add_f32_e32 v2, 0, v2
	v_cvt_pk_bf16_f32 v164, v110, v111
	v_cvt_pk_bf16_f32 v165, v112, v113
	s_add_i32 s0, s35, -2
	v_max_f32_e32 v17, v147, v147
	v_max_f32_e32 v110, v146, v146
	s_min_i32 s0, s0, s91
	v_max_f32_e32 v17, v110, v17
	s_ashr_i32 s1, s0, 31
	s_nop 0
	v_max3_f32 v110, v148, v149, v131
	v_max3_f32 v17, v17, v130, v132
	s_lshl_b64 s[0:1], s[0:1], 17
	v_max3_f32 v17, v17, v133, v150
	v_max3_f32 v110, v110, v152, v153
	s_add_u32 s0, s87, s0
	v_max3_f32 v17, v17, v151, v134
	v_max3_f32 v110, v110, v136, v137
	s_addc_u32 s1, s88, s1
	s_add_i32 s4, s36, s81
	v_max3_f32 v17, v17, v135, v154
	v_max3_f32 v110, v110, v156, v157
	s_mov_b32 s5, m0
	s_mov_b32 m0, s4
	s_nop 4
	global_load_lds_dwordx4 v237, s[0:1]
	s_mov_b32 m0, s5
	s_add_u32 s0, s0, 0x80
	v_max3_f32 v17, v17, v155, v138
	v_max3_f32 v110, v110, v140, v141
	s_addc_u32 s1, s1, 0
	s_add_i32 s4, s36, s82
	s_mov_b32 s5, m0
	s_mov_b32 m0, s4
	s_nop 4
	global_load_lds_dwordx4 v237, s[0:1]
	s_mov_b32 m0, s5
	s_add_i32 s0, s35, -4
	v_max3_f32 v17, v17, v139, v158
	v_max3_f32 v110, v110, v160, v161
	s_min_i32 s0, s0, s91
	v_max3_f32 v17, v17, v159, v142
	v_max3_f32 v110, v110, v144, v145
	s_ashr_i32 s1, s0, 31
	v_max3_f32 v17, v17, v143, v110
	s_lshl_b64 s[0:1], s[0:1], 17
	v_mov_b32_e32 v110, v17
	s_add_u32 s0, s89, s0
	s_nop 0
	v_permlane32_swap_b32_e32 v17, v110
	s_addc_u32 s1, s90, s1
	s_add_i32 s4, s34, s80
	v_max_f32_e32 v110, v110, v110
	v_max_f32_e32 v17, v17, v17
	s_mov_b32 s5, m0
	s_mov_b32 m0, s4
	s_nop 4
	global_load_lds_dwordx4 v238, s[0:1]
	s_mov_b32 m0, s5
	s_add_u32 s0, s0, 0x80
	v_max_f32_e32 v17, v17, v110
	s_addc_u32 s1, s1, 0
	s_add_i32 s4, s34, s84
	s_mov_b32 s5, m0
	s_mov_b32 m0, s4
	s_nop 4
	global_load_lds_dwordx4 v238, s[0:1]
	s_mov_b32 m0, s5
	v_cmp_lt_f32_e32 vcc, s62, v17
	s_cmp_lg_u64 vcc, 0
	v_add_f32_e32 v2, v248, v2
	s_cselect_b64 s[0:1], -1, 0
	s_cbranch_vccnz .LBB0_1076

.LBB0_1071:
	s_waitcnt lgkmcnt(0)
	v_mfma_f32_32x32x16_bf16 v[114:129], v[98:101], v[198:201], v[82:97]
	s_add_i32 s0, s34, 0x4000
	s_cmpk_lg_u32 s34, 0x8000
	s_cselect_b32 s92, s0, 0
	v_add_u32_e32 v16, s36, v246
	ds_read_b64_tr_b16 v[180:181], v16 offset:49664
	ds_read_b64_tr_b16 v[178:179], v16 offset:49152
	v_add_f32_e32 v17, v146, v147
	v_add_f32_e32 v17, v148, v17
	v_add_f32_e32 v17, v149, v17
	v_add_f32_e32 v17, v150, v17
	v_add_f32_e32 v17, v151, v17
	v_cvt_pk_bf16_f32 v174, v146, v147
	v_cvt_pk_bf16_f32 v175, v148, v149
	ds_read_b64_tr_b16 v[148:149], v16 offset:53760
	ds_read_b64_tr_b16 v[146:147], v16 offset:53248
	ds_read_b128 v[202:205], v244 offset:1024
	v_mfma_f32_32x32x16_bf16 v[98:113], v[194:197], v[198:201], v[82:97]
	v_add_f32_e32 v17, v152, v17
	v_add_f32_e32 v17, v153, v17
	v_add_f32_e32 v17, v154, v17
	v_add_f32_e32 v17, v155, v17
	v_cvt_pk_bf16_f32 v176, v150, v151
	v_cvt_pk_bf16_f32 v177, v152, v153
	ds_read_b64_tr_b16 v[150:151], v16 offset:50176
	ds_read_b64_tr_b16 v[152:153], v16 offset:50688
	s_waitcnt lgkmcnt(2)
	v_mfma_f32_32x32x16_bf16 v[114:129], v[190:193], v[202:205], v[114:129]
	v_add_f32_e32 v17, v156, v17
	v_add_f32_e32 v17, v157, v17
	v_add_f32_e32 v17, v158, v17
	v_add_f32_e32 v17, v159, v17
	v_cvt_pk_bf16_f32 v170, v154, v155
	v_cvt_pk_bf16_f32 v171, v156, v157
	ds_read_b64_tr_b16 v[156:157], v16 offset:54784
	ds_read_b64_tr_b16 v[154:155], v16 offset:54272
	ds_read_b128 v[190:193], v244 offset:2048
	v_mfma_f32_32x32x16_bf16 v[98:113], v[186:189], v[202:205], v[98:113]
	v_add_f32_e32 v17, v160, v17
	v_add_f32_e32 v17, v161, v17
	v_add_f32_e32 v17, v130, v17
	v_add_f32_e32 v17, v131, v17
	v_cvt_pk_bf16_f32 v172, v158, v159
	v_cvt_pk_bf16_f32 v173, v160, v161
	ds_read_b64_tr_b16 v[158:159], v16 offset:51200
	ds_read_b64_tr_b16 v[160:161], v16 offset:51712
	s_waitcnt lgkmcnt(2)
	v_mfma_f32_32x32x16_bf16 v[114:129], v[182:185], v[190:193], v[114:129]
	v_add_f32_e32 v17, v132, v17
	v_add_f32_e32 v17, v133, v17
	v_add_f32_e32 v17, v134, v17
	v_add_f32_e32 v17, v135, v17
	v_cvt_pk_bf16_f32 v166, v130, v131
	v_cvt_pk_bf16_f32 v167, v132, v133
	ds_read_b64_tr_b16 v[132:133], v16 offset:55808
	ds_read_b64_tr_b16 v[130:131], v16 offset:55296
	ds_read_b128 v[182:185], v244 offset:3072
	v_mfma_f32_32x32x16_bf16 v[98:113], v[12:15], v[190:193], v[98:113]
	v_add_f32_e32 v17, v136, v17
	v_add_f32_e32 v17, v137, v17
	v_add_f32_e32 v17, v138, v17
	v_add_f32_e32 v17, v139, v17
	v_cvt_pk_bf16_f32 v168, v134, v135
	v_cvt_pk_bf16_f32 v169, v136, v137
	ds_read_b64_tr_b16 v[12:13], v16 offset:52224
	ds_read_b64_tr_b16 v[14:15], v16 offset:52736
	s_waitcnt lgkmcnt(2)
	v_mfma_f32_32x32x16_bf16 v[114:129], v[8:11], v[182:185], v[114:129]
	v_add_f32_e32 v17, v140, v17
	v_add_f32_e32 v17, v141, v17
	v_add_f32_e32 v17, v142, v17
	v_add_f32_e32 v17, v143, v17
	v_cvt_pk_bf16_f32 v162, v138, v139
	v_cvt_pk_bf16_f32 v163, v140, v141
	ds_read_b64_tr_b16 v[8:9], v16 offset:56320
	ds_read_b64_tr_b16 v[10:11], v16 offset:56832
	v_mfma_f32_32x32x16_bf16 v[98:113], v[4:7], v[182:185], v[98:113]
	v_add_f32_e32 v17, v144, v17
	v_add_f32_e32 v17, v145, v17
	v_add_f32_e32 v17, 0, v17
	v_cvt_pk_bf16_f32 v164, v142, v143
	v_cvt_pk_bf16_f32 v165, v144, v145
	s_add_i32 s0, s35, -1
	v_max_f32_e32 v4, v115, v115
	v_max_f32_e32 v5, v114, v114
	s_min_i32 s0, s0, s91
	v_max_f32_e32 v4, v5, v4
	s_ashr_i32 s1, s0, 31
	s_nop 0
	v_max3_f32 v5, v116, v117, v99
	v_max3_f32 v4, v4, v98, v100
	s_lshl_b64 s[0:1], s[0:1], 17
	v_max3_f32 v4, v4, v101, v118
	v_max3_f32 v5, v5, v120, v121
	s_add_u32 s0, s87, s0
	v_max3_f32 v4, v4, v119, v102
	v_max3_f32 v5, v5, v104, v105
	s_addc_u32 s1, s88, s1
	s_add_i32 s4, s34, s81
	v_max3_f32 v4, v4, v103, v122
	v_max3_f32 v5, v5, v124, v125
	s_mov_b32 s5, m0
	s_mov_b32 m0, s4
	s_nop 4
	global_load_lds_dwordx4 v237, s[0:1]
	s_mov_b32 m0, s5
	s_add_u32 s0, s0, 0x80
	v_max3_f32 v4, v4, v123, v106
	v_max3_f32 v5, v5, v108, v109
	s_addc_u32 s1, s1, 0
	s_add_i32 s93, s35, -3
	v_max3_f32 v4, v4, v107, v126
	v_max3_f32 v5, v5, v128, v129
	s_add_i32 s4, s34, s82
	s_mov_b32 s5, m0
	s_mov_b32 m0, s4
	s_nop 4
	global_load_lds_dwordx4 v237, s[0:1]
	s_mov_b32 m0, s5
	s_min_i32 s0, s93, s91
	v_max3_f32 v4, v4, v127, v110
	v_max3_f32 v5, v5, v112, v113
	s_ashr_i32 s1, s0, 31
	v_add_f32_e32 v248, v2, v17
	v_max3_f32 v2, v4, v111, v5
	s_lshl_b64 s[0:1], s[0:1], 17
	v_mov_b32_e32 v4, v2
	s_add_u32 s0, s89, s0
	s_nop 0
	v_permlane32_swap_b32_e32 v2, v4
	s_addc_u32 s1, s90, s1
	s_add_i32 s4, s92, s80
	v_max_f32_e32 v4, v4, v4
	v_max_f32_e32 v2, v2, v2
	s_mov_b32 s5, m0
	s_mov_b32 m0, s4
	s_nop 4
	global_load_lds_dwordx4 v238, s[0:1]
	s_mov_b32 m0, s5
	s_add_u32 s0, s0, 0x80
	v_max_f32_e32 v2, v2, v4
	s_addc_u32 s1, s1, 0
	s_add_i32 s4, s92, s84
	s_mov_b32 s5, m0
	s_mov_b32 m0, s4
	s_nop 4
	global_load_lds_dwordx4 v238, s[0:1]
	s_mov_b32 m0, s5
	v_cmp_lt_f32_e32 vcc, s62, v2
	s_cmp_lg_u64 vcc, 0
	s_cselect_b64 s[0:1], -1, 0
	s_cbranch_vccnz .LBB0_1079
